# K56 + both attention-loop edits stacked: v_permlane32_swap for the xor-32 exchanges and V staging / K prefetch moved to the first consumer
# baseline (speedup 1.0000x reference)
.LBB0_627:
	s_add_i32 s2, s39, s46
	s_addk_i32 s2, 0xff80
	s_cmp_lt_i32 s2, 0
	s_cbranch_scc1 .Lmy_kpf_skip
	v_add_u32_e32 v34, s46, v89
	v_add_u32_e32 v0, 0xffffff80, v34
	v_lshlrev_b64 v[38:39], s19, v[0:1]
	v_add_u32_e32 v0, 0xffffff88, v34
	v_lshlrev_b64 v[114:115], s19, v[0:1]
	v_add_u32_e32 v0, 0xffffff90, v34
	v_lshlrev_b64 v[150:151], s19, v[0:1]
	v_add_u32_e32 v0, 0xffffff98, v34
	v_lshlrev_b64 v[152:153], s19, v[0:1]
	v_mad_u64_u32 v[40:41], s[2:3], v38, s20, v[98:99]
	v_mad_u32_u24 v41, v39, s20, v41
	v_and_b32_e32 v38, 64, v125
	global_load_dwordx4 v[146:149], v[40:41], off offset:3072
	v_add_u32_e32 v96, 64, v38
	v_add_u32_e32 v175, v132, v67
	v_add_u32_e32 v176, v132, v66
	v_cvt_f32_i32_e32 v157, v175
	v_cvt_f32_i32_e32 v156, v176
	v_add_u32_e32 v177, v69, v132
	v_add_u32_e32 v178, v68, v132
	v_cvt_f32_i32_e32 v159, v177
	v_cvt_f32_i32_e32 v158, v178
	v_xor_b32_e32 v0, 32, v125
	v_add_u32_e32 v168, v74, v132
	v_add_u32_e32 v179, v71, v132
	v_add_u32_e32 v180, v70, v132
	v_cvt_f32_i32_e32 v91, v168
	v_cvt_f32_i32_e32 v161, v179
	v_cvt_f32_i32_e32 v160, v180
	v_cmp_lt_i32_e32 vcc, v0, v96
	v_pk_mul_f32 v[156:157], v[102:103], v[156:157]
	v_pk_mul_f32 v[158:159], v[102:103], v[158:159]
	v_cndmask_b32_e32 v0, v125, v0, vcc
	v_cmp_gt_u32_e32 vcc, s21, v175
	v_lshlrev_b32_e32 v184, 2, v0
	v_add_u32_e32 v163, v75, v132
	v_mad_u64_u32 v[166:167], s[2:3], v114, s20, v[98:99]
	v_pk_mul_f32 v[160:161], v[102:103], v[160:161]
	v_mad_u32_u24 v167, v115, s20, v167
	v_mad_u64_u32 v[114:115], s[2:3], v150, s20, v[98:99]
	v_mad_u32_u24 v115, v151, s20, v115
	v_mad_u64_u32 v[150:151], s[2:3], v152, s20, v[98:99]
	v_mov_b32_e32 v155, v97
	v_add_u32_e32 v170, v76, v132
	v_mad_u32_u24 v151, v153, s20, v151
	global_load_dwordx4 v[186:189], v[166:167], off offset:3072
	global_load_dwordx4 v[190:193], v[114:115], off offset:3072
	global_load_dwordx4 v[194:197], v[150:151], off offset:3072
	v_mov_b32_e32 v117, v97
	v_add_u32_e32 v169, v77, v132
	v_mov_b32_e32 v113, v97
	v_add_u32_e32 v172, v78, v132
	v_mov_b32_e32 v111, v97
	v_add_u32_e32 v174, v80, v132
	v_mov_b32_e32 v109, v97
	v_add_u32_e32 v171, v79, v132
	v_mov_b32_e32 v107, v97
	v_add_u32_e32 v173, v81, v132
	v_mov_b32_e32 v105, v97
	v_add_u32_e32 v182, v73, v132
	v_add_u32_e32 v183, v72, v132
	v_cvt_f32_i32_e32 v165, v182
	v_cvt_f32_i32_e32 v164, v183
	s_waitcnt vmcnt(7)
	v_mfma_f32_32x32x16_bf16 v[34:49], v[212:215], v[50:53], 0
	s_waitcnt vmcnt(6)
	v_mfma_f32_32x32x16_bf16 v[34:49], v[216:219], v[54:57], v[34:49]
	s_waitcnt vmcnt(5)
	v_mfma_f32_32x32x16_bf16 v[34:49], v[220:223], v[58:61], v[34:49]
	s_waitcnt vmcnt(4)
	v_mfma_f32_32x32x16_bf16 v[34:49], v[224:227], v[62:65], v[34:49]
	s_nop 11
	v_mov_b32_e32 v96, v42
	v_mov_b32_e32 v116, v43
	v_mov_b32_e32 v42, v34
	v_mov_b32_e32 v43, v36
	v_pk_fma_f32 v[42:43], v[42:43], s[16:17], v[156:157] op_sel_hi:[1,0,1] neg_lo:[0,0,1] neg_hi:[0,0,1]
	v_mov_b32_e32 v36, v35
	v_cndmask_b32_e32 v0, v126, v43, vcc
	v_cmp_gt_u32_e32 vcc, s21, v176
	v_mov_b32_e32 v110, v46
	v_pk_fma_f32 v[36:37], v[36:37], s[16:17], v[158:159] op_sel_hi:[1,0,1] neg_lo:[0,0,1] neg_hi:[0,0,1]
	v_cndmask_b32_e32 v46, v126, v42, vcc
	v_cmp_gt_u32_e32 vcc, s21, v177
	v_mov_b32_e32 v108, v47
	v_mov_b32_e32 v34, v38
	v_mov_b32_e32 v35, v40
	v_mov_b32_e32 v40, v39
	v_pk_mul_f32 v[38:39], v[96:97], v[90:91]
	v_cvt_f32_i32_e32 v91, v163
	v_cndmask_b32_e32 v47, v126, v37, vcc
	v_cmp_gt_u32_e32 vcc, s21, v178
	v_mov_b32_e32 v106, v48
	v_pk_fma_f32 v[34:35], v[34:35], s[16:17], v[160:161] op_sel_hi:[1,0,1] neg_lo:[0,0,1] neg_hi:[0,0,1]
	v_cndmask_b32_e32 v48, v126, v36, vcc
	v_cmp_gt_u32_e32 vcc, s21, v179
	v_mov_b32_e32 v104, v49
	v_mov_b32_e32 v154, v44
	v_cndmask_b32_e32 v49, v126, v35, vcc
	v_cmp_gt_u32_e32 vcc, s21, v180
	v_mov_b32_e32 v112, v45
	v_mov_b32_e32 v44, v38
	v_cndmask_b32_e32 v96, v126, v34, vcc
	v_max3_f32 v34, v46, s22, v48
	v_max3_f32 v114, v34, v0, v47
	v_pk_mul_f32 v[34:35], v[154:155], v[90:91]
	v_cvt_f32_i32_e32 v91, v170
	v_mov_b32_e32 v45, v34
	v_mov_b32_e32 v34, v39
	v_pk_add_f32 v[34:35], v[44:45], v[34:35] neg_lo:[0,1] neg_hi:[0,1]
	v_pk_mul_f32 v[36:37], v[116:117], v[90:91]
	v_cvt_f32_i32_e32 v91, v169
	v_cmp_gt_u32_e32 vcc, s21, v163
	v_mov_b32_e32 v38, v36
	s_nop 0
	v_cndmask_b32_e32 v44, v126, v35, vcc
	v_cmp_gt_u32_e32 vcc, s21, v168
	s_nop 1
	v_cndmask_b32_e32 v45, v126, v34, vcc
	v_pk_mul_f32 v[34:35], v[112:113], v[90:91]
	v_cvt_f32_i32_e32 v91, v172
	v_mov_b32_e32 v39, v34
	v_mov_b32_e32 v34, v37
	v_pk_add_f32 v[34:35], v[38:39], v[34:35] neg_lo:[0,1] neg_hi:[0,1]
	v_pk_mul_f32 v[36:37], v[110:111], v[90:91]
	v_cvt_f32_i32_e32 v91, v174
	v_cmp_gt_u32_e32 vcc, s21, v169
	v_pk_mul_f32 v[38:39], v[108:109], v[90:91]
	v_cvt_f32_i32_e32 v91, v171
	v_cndmask_b32_e32 v110, v126, v35, vcc
	v_cmp_gt_u32_e32 vcc, s21, v170
	v_pk_mul_f32 v[42:43], v[106:107], v[90:91]
	v_cvt_f32_i32_e32 v91, v173
	v_cndmask_b32_e32 v108, v126, v34, vcc
	v_mov_b32_e32 v34, v36
	v_mov_b32_e32 v35, v42
	v_mov_b32_e32 v42, v37
	v_pk_add_f32 v[34:35], v[34:35], v[42:43] neg_lo:[0,1] neg_hi:[0,1]
	v_cmp_gt_u32_e32 vcc, s21, v171
	v_mov_b32_e32 v36, v38
	s_nop 0
	v_cndmask_b32_e32 v42, v126, v35, vcc
	v_cmp_gt_u32_e32 vcc, s21, v172
	s_nop 1
	v_cndmask_b32_e32 v43, v126, v34, vcc
	v_pk_mul_f32 v[34:35], v[104:105], v[90:91]
	v_cmp_gt_u32_e32 vcc, s21, v173
	v_mov_b32_e32 v37, v34
	v_mov_b32_e32 v34, v39
	v_pk_add_f32 v[34:35], v[36:37], v[34:35] neg_lo:[0,1] neg_hi:[0,1]
	s_nop 0
	v_cndmask_b32_e32 v91, v126, v35, vcc
	v_cmp_gt_u32_e32 vcc, s21, v174
	s_nop 1
	v_cndmask_b32_e32 v104, v126, v34, vcc
	v_pk_mul_f32 v[34:35], v[102:103], v[164:165]
	v_cmp_gt_u32_e32 vcc, s21, v182
	v_pk_fma_f32 v[34:35], v[40:41], s[16:17], v[34:35] op_sel_hi:[1,0,1] neg_lo:[0,0,1] neg_hi:[0,0,1]
	s_nop 0
	v_cndmask_b32_e32 v105, v126, v35, vcc
	v_cmp_gt_u32_e32 vcc, s21, v183
	s_nop 1
	v_cndmask_b32_e32 v106, v126, v34, vcc
	v_max3_f32 v34, v114, v96, v106
	v_max3_f32 v34, v34, v49, v105
	v_max3_f32 v34, v34, v45, v108
	v_max3_f32 v34, v34, v44, v110
	v_max3_f32 v34, v34, v43, v104
	v_max3_f32 v34, v34, v42, v91
	v_mov_b32_e32 v35, v34
	s_nop 1
	v_permlane32_swap_b32_e32 v35, v34
	v_max3_f32 v107, v133, v34, v35
	v_sub_f32_e32 v34, v46, v107
	v_sub_f32_e32 v111, v133, v107
	v_mov_b32_e32 v133, v107
	v_exp_f32_e32 v109, v34
	s_waitcnt vmcnt(3)
	ds_write_b128 v123, v[146:149]
	s_waitcnt vmcnt(2)
	ds_write_b128 v123, v[186:189] offset:1024
	s_waitcnt vmcnt(1)
	ds_write_b128 v123, v[190:193] offset:2048
	s_waitcnt vmcnt(0)
	ds_write_b128 v123, v[194:197] offset:3072
	s_cmp_eq_u32 s56, 1
	s_cbranch_scc1 .Lmy_kpf_b
	s_add_i32 s98, s46, 32
	s_cmpk_lg_i32 s98, 0xa0
	s_cselect_b32 s98, s98, 0
	s_add_i32 s99, s39, s98
	s_addk_i32 s99, 0xff80
	s_cmp_lt_i32 s99, 0
	s_cbranch_scc1 .Lmy_kpf_b
	v_add_u32_e32 v228, s98, v131
	v_mov_b32_e32 v229, 0
	v_lshlrev_b64 v[230:231], s19, v[228:229]
	v_mad_u64_u32 v[232:233], s[100:101], v230, s20, v[100:101]
	v_mad_u32_u24 v233, v231, s20, v233
	global_load_dwordx4 v[212:215], v[232:233], off offset:1536
	global_load_dwordx4 v[216:219], v[232:233], off offset:1568
	global_load_dwordx4 v[220:223], v[232:233], off offset:1600
	global_load_dwordx4 v[224:227], v[232:233], off offset:1632
.Lmy_kpf_b:
	s_waitcnt lgkmcnt(0)
	ds_read_b64_tr_b16 v[38:39], v124
	ds_read_b64_tr_b16 v[40:41], v124 offset:1024
	ds_read_b64_tr_b16 v[36:37], v124 offset:1088
	ds_read_b64_tr_b16 v[34:35], v124 offset:64
	v_sub_f32_e32 v112, v48, v107
	s_nop 1
	v_sub_f32_e32 v113, v0, v107
	v_exp_f32_e32 v112, v112
	s_nop 0
	v_exp_f32_e32 v113, v113
	v_cmp_lt_f32_e32 vcc, s23, v0
	v_sub_f32_e32 v0, v47, v107
	v_cmp_lt_f32_e64 s[2:3], s23, v46
	v_cndmask_b32_e32 v113, 0, v113, vcc
	s_nop 0
	v_cndmask_b32_e64 v46, 0, v109, s[2:3]
	s_nop 0
	v_exp_f32_e32 v0, v0
	v_cmp_lt_f32_e32 vcc, s23, v47
	s_nop 0
	s_nop 0
	v_cndmask_b32_e32 v47, 0, v0, vcc
	v_cmp_lt_f32_e32 vcc, s23, v48
	v_sub_f32_e32 v0, v96, v107
	s_nop 0
	v_cndmask_b32_e32 v48, 0, v112, vcc
	s_nop 1
	v_sub_f32_e32 v109, v49, v107
	v_exp_f32_e32 v0, v0
	s_nop 0
	v_exp_f32_e32 v109, v109
	v_cmp_lt_f32_e32 vcc, s23, v49
	s_nop 1
	v_cndmask_b32_e32 v49, 0, v109, vcc
	v_cmp_lt_f32_e32 vcc, s23, v96
	s_nop 1
	v_cndmask_b32_e32 v96, 0, v0, vcc
	v_sub_f32_e32 v0, v106, v107
	s_nop 1
	v_sub_f32_e32 v109, v105, v107
	v_exp_f32_e32 v0, v0
	s_nop 0
	v_exp_f32_e32 v109, v109
	v_cmp_lt_f32_e32 vcc, s23, v105
	s_nop 1
	v_cndmask_b32_e32 v105, 0, v109, vcc
	v_cmp_lt_f32_e32 vcc, s23, v106
	s_nop 1
	v_cndmask_b32_e32 v106, 0, v0, vcc
	v_sub_f32_e32 v0, v45, v107
	s_nop 1
	v_sub_f32_e32 v109, v44, v107
	v_exp_f32_e32 v0, v0
	s_nop 0
	v_exp_f32_e32 v109, v109
	v_cmp_lt_f32_e32 vcc, s23, v44
	s_nop 1
	v_cndmask_b32_e32 v109, 0, v109, vcc
	v_cmp_lt_f32_e32 vcc, s23, v45
	s_nop 1
	v_cndmask_b32_e32 v112, 0, v0, vcc
	v_sub_f32_e32 v0, v108, v107
	s_nop 1
	v_sub_f32_e32 v44, v110, v107
	v_exp_f32_e32 v0, v0
	s_nop 0
	v_exp_f32_e32 v44, v44
	v_cmp_lt_f32_e32 vcc, s23, v110
	s_nop 1
	v_cndmask_b32_e32 v110, 0, v44, vcc
	v_cmp_lt_f32_e32 vcc, s23, v108
	s_nop 1
	v_cndmask_b32_e32 v108, 0, v0, vcc
	v_sub_f32_e32 v0, v43, v107
	s_nop 1
	v_sub_f32_e32 v44, v42, v107
	v_exp_f32_e32 v0, v0
	s_nop 0
	v_exp_f32_e32 v44, v44
	v_cmp_lt_f32_e32 vcc, s23, v42
	v_bfe_u32 v45, v48, 16, 1
	s_nop 0
	v_cndmask_b32_e32 v114, 0, v44, vcc
	v_cmp_lt_f32_e32 vcc, s23, v43
	v_bfe_u32 v44, v47, 16, 1
	s_nop 0
	v_cndmask_b32_e32 v115, 0, v0, vcc
	v_sub_f32_e32 v0, v104, v107
	s_nop 1
	v_sub_f32_e32 v42, v91, v107
	v_exp_f32_e32 v0, v0
	s_nop 0
	v_exp_f32_e32 v42, v42
	v_cmp_lt_f32_e32 vcc, s23, v91
	v_bfe_u32 v43, v106, 16, 1
	v_add3_u32 v43, v106, v43, s28
	v_cndmask_b32_e32 v91, 0, v42, vcc
	v_cmp_lt_f32_e32 vcc, s23, v104
	s_nop 1
	v_cndmask_b32_e32 v104, 0, v0, vcc
	v_add_f32_e32 v0, v46, v48
	v_add_f32_e32 v0, v113, v0
	v_add_f32_e32 v0, v47, v0
	v_add_f32_e32 v0, v96, v0
	v_add_f32_e32 v0, v106, v0
	v_add_f32_e32 v0, v49, v0
	v_add_f32_e32 v0, v105, v0
	v_add_f32_e32 v0, v112, v0
	v_add_f32_e32 v0, v108, v0
	v_add_f32_e32 v0, v109, v0
	v_mov_b32_e32 v42, v111
	v_add_f32_e32 v0, v110, v0
	v_exp_f32_e32 v42, v42
	v_add_f32_e32 v0, v115, v0
	v_add_f32_e32 v0, v104, v0
	v_add_f32_e32 v111, v114, v0
	v_mov_b32_e32 v0, v42
	v_bfe_u32 v42, v105, 16, 1
	v_add3_u32 v48, v48, v45, s28
	v_add3_u32 v47, v47, v44, s28
	v_add3_u32 v42, v105, v42, s28
	v_bfe_u32 v44, v46, 16, 1
	v_bfe_u32 v45, v113, 16, 1
	v_bfe_u32 v105, v96, 16, 1
	v_bfe_u32 v106, v49, 16, 1
	v_add3_u32 v49, v49, v106, s28
	v_add3_u32 v96, v96, v105, s28
	v_add3_u32 v45, v113, v45, s28
	v_add3_u32 v44, v46, v44, s28
	v_lshrrev_b32_e32 v46, 16, v44
	v_lshrrev_b32_e32 v105, 16, v45
	v_lshrrev_b32_e32 v44, 16, v96
	v_lshrrev_b32_e32 v45, 16, v49
	v_pk_mul_f32 v[32:33], v[32:33], v[0:1] op_sel_hi:[1,0]
	v_pk_mul_f32 v[30:31], v[30:31], v[0:1] op_sel_hi:[1,0]
	v_pk_mul_f32 v[28:29], v[28:29], v[0:1] op_sel_hi:[1,0]
	v_pk_mul_f32 v[26:27], v[26:27], v[0:1] op_sel_hi:[1,0]
	v_pk_mul_f32 v[24:25], v[24:25], v[0:1] op_sel_hi:[1,0]
	v_pk_mul_f32 v[22:23], v[22:23], v[0:1] op_sel_hi:[1,0]
	v_pk_mul_f32 v[20:21], v[20:21], v[0:1] op_sel_hi:[1,0]
	v_pk_mul_f32 v[18:19], v[18:19], v[0:1] op_sel_hi:[1,0]
	v_pk_mul_f32 v[16:17], v[16:17], v[0:1] op_sel_hi:[1,0]
	v_and_or_b32 v45, v42, s29, v45
	v_and_or_b32 v44, v43, s29, v44
	v_and_or_b32 v43, v47, s29, v105
	v_and_or_b32 v42, v48, s29, v46
	v_pk_mul_f32 v[14:15], v[14:15], v[0:1] op_sel_hi:[1,0]
	v_pk_mul_f32 v[12:13], v[12:13], v[0:1] op_sel_hi:[1,0]
	v_pk_mul_f32 v[10:11], v[10:11], v[0:1] op_sel_hi:[1,0]
	v_pk_mul_f32 v[8:9], v[8:9], v[0:1] op_sel_hi:[1,0]
	v_pk_mul_f32 v[6:7], v[6:7], v[0:1] op_sel_hi:[1,0]
	v_pk_mul_f32 v[4:5], v[4:5], v[0:1] op_sel_hi:[1,0]
	v_pk_mul_f32 v[2:3], v[2:3], v[0:1] op_sel_hi:[1,0]
	s_waitcnt lgkmcnt(2)
	v_mfma_f32_32x32x16_bf16 v[18:33], v[38:41], v[42:45], v[18:33]
	s_waitcnt lgkmcnt(0)
	v_mfma_f32_32x32x16_bf16 v[2:17], v[34:37], v[42:45], v[2:17]
	v_bfe_u32 v34, v91, 16, 1
	v_bfe_u32 v35, v104, 16, 1
	v_bfe_u32 v36, v110, 16, 1
	v_bfe_u32 v37, v108, 16, 1
	v_add3_u32 v38, v108, v37, s28
	v_add3_u32 v39, v110, v36, s28
	v_add3_u32 v40, v104, v35, s28
	v_add3_u32 v41, v91, v34, s28
	v_bfe_u32 v34, v112, 16, 1
	v_bfe_u32 v35, v109, 16, 1
	v_bfe_u32 v36, v115, 16, 1
	v_bfe_u32 v37, v114, 16, 1
	v_add3_u32 v42, v114, v37, s28
	v_add3_u32 v43, v115, v36, s28
	v_add3_u32 v35, v109, v35, s28
	v_add3_u32 v34, v112, v34, s28
	v_lshrrev_b32_e32 v44, 16, v34
	v_lshrrev_b32_e32 v45, 16, v35
	ds_read_b64_tr_b16 v[34:35], v124 offset:2048
	ds_read_b64_tr_b16 v[36:37], v124 offset:3072
	v_lshrrev_b32_e32 v43, 16, v43
	v_lshrrev_b32_e32 v42, 16, v42
	v_and_or_b32 v41, v41, s29, v42
	v_and_or_b32 v40, v40, s29, v43
	v_and_or_b32 v39, v39, s29, v45
	v_and_or_b32 v38, v38, s29, v44
	ds_read_b64_tr_b16 v[44:45], v124 offset:3136
	ds_read_b64_tr_b16 v[42:43], v124 offset:2112
	s_waitcnt lgkmcnt(2)
	v_mfma_f32_32x32x16_bf16 v[18:33], v[34:37], v[38:41], v[18:33]
	v_add_f32_e32 v34, v91, v111
	v_mov_b32_e32 v35, v34
	s_nop 1
	v_permlane32_swap_b32_e32 v35, v34
	s_waitcnt lgkmcnt(0)
	s_waitcnt lgkmcnt(0)
	v_add_f32_e32 v34, v34, v35
	v_mfma_f32_32x32x16_bf16 v[2:17], v[42:45], v[38:41], v[2:17]
	v_fmac_f32_e32 v34, v130, v0
	v_mov_b32_e32 v130, v34
	s_branch .LBB0_626
